# last-iteration exit path: leading half's barrier issued right after the last MFMA (before counter updates)
# baseline (speedup 1.0000x reference)
; __device__ __forceinline__ u32x4 pack8(const f32x4& a, const f32x4& b) { u32x4 w; w.x = pk2(a[0], a[1]); w.y = pk2(a[2], a[3]); w.z = pk2(b[0], b[1]); w.w = pk2(b[2], b[3]); return w; }
; __device__ __forceinline__ void unpack8(const u32x4& w, f32x4& a, f32x4& b) { a[0] = bflo(w.x); a[1] = bfhi(w.x); a[2] = bflo(w.y); a[3] = bfhi(w.y); b[0] = bflo(w.z); b[1] = bfhi(w.z); b[2] = bflo(w.w); b[3] = bfhi(w.w); }
;     __device__ __forceinline__ void operator()(const f32x4 (&acc)[2][2][4][2], const Unit& u, int wr, int wc, int fr, int fq) const {
;         const int row0 = u.pm * BM + wr * 64 + fr, col0 = u.pn * BM + 32 * wc + 8 * fq;
; #pragma unroll
;         for (int ai = 0; ai < 2; ++ai) {
;             u32x4 b[4][2];
; #pragma unroll
;             for (int m = 0; m < 4; ++m)
; #pragma unroll
;                 for (int bj = 0; bj < 2; ++bj) b[m][bj] = *(const u32x4*)(xb + (size_t)(row0 + ai * HALF + m * 16) * DM + col0 + 128 * bj);
; #pragma unroll
;             for (int m = 0; m < 4; ++m) { const int row = row0 + ai * HALF + m * 16; const size_t off = (size_t)row * DM + col0; float ss = 0.f;
; #pragma unroll
;                 for (int bj = 0; bj < 2; ++bj) { f32x4 p0, p1; unpack8(b[m][bj], p0, p1); const f32x4 x0 = p0 + acc[ai][bj][m][0], x1 = p1 + acc[ai][bj][m][1];
;                     ss += ((x0[0] * x0[0] + x0[1] * x0[1]) + (x0[2] * x0[2] + x0[3] * x0[3])) + ((x1[0] * x1[0] + x1[1] * x1[1]) + (x1[2] * x1[2] + x1[3] * x1[3]));
;                     if (fout) { *(f32x4*)(fout + off + 128 * bj) = x0; *(f32x4*)(fout + off + 128 * bj + 4) = x1; } else *(u32x4*)(xb + off + 128 * bj) = pack8(x0, x1); }
.Lnb3_g1:
	s_setprio 0
	s_add_u32 s44, s44, 0x100
	s_addc_u32 s45, s45, 0
	s_add_u32 s19, s19, 0x100
	s_addc_u32 s20, s20, 0
	s_cmp_ge_u32 s66, s73
	s_mov_b32 s46, s66
.LBB0_66:
	v_lshl_add_u32 v170, s18, 8, v182
	v_lshl_or_b32 v168, s8, 8, v184
	v_ashrrev_i32_e32 v169, 31, v168
	v_ashrrev_i32_e32 v171, 31, v170
	v_lshl_add_u64 v[166:167], v[168:169], 1, s[30:31]
	v_lshlrev_b64 v[128:129], 11, v[170:171]
	v_or_b32_e32 v176, 16, v170
	v_lshl_add_u64 v[128:129], v[166:167], 0, v[128:129]
	v_ashrrev_i32_e32 v177, 31, v176
	global_load_dwordx4 v[186:189], v[128:129], off
	global_load_dwordx4 v[152:155], v[128:129], off offset:256
	v_lshlrev_b64 v[128:129], 11, v[176:177]
	v_or_b32_e32 v174, 32, v170
	v_lshl_add_u64 v[128:129], v[166:167], 0, v[128:129]
	v_ashrrev_i32_e32 v175, 31, v174
	global_load_dwordx4 v[148:151], v[128:129], off
	global_load_dwordx4 v[144:147], v[128:129], off offset:256
	v_lshlrev_b64 v[128:129], 11, v[174:175]
	v_or_b32_e32 v172, 48, v170
	v_lshl_add_u64 v[128:129], v[166:167], 0, v[128:129]
	v_ashrrev_i32_e32 v173, 31, v172
	global_load_dwordx4 v[140:143], v[128:129], off
	global_load_dwordx4 v[136:139], v[128:129], off offset:256
	v_lshlrev_b64 v[128:129], 11, v[172:173]
	v_lshl_add_u64 v[128:129], v[166:167], 0, v[128:129]
	global_load_dwordx4 v[132:135], v[128:129], off
	s_nop 0
	global_load_dwordx4 v[128:131], v[128:129], off offset:256
	v_cndmask_b32_e64 v178, 0, 1, s[58:59]
	v_cmp_ne_u32_e64 s[44:45], 1, v178
	v_lshlrev_b64 v[178:179], 10, v[170:171]
	v_lshl_add_u64 v[180:181], v[178:179], 0, v[168:169]
	s_andn2_b64 vcc, exec, s[58:59]
	v_lshl_add_u64 v[180:181], v[180:181], 2, s[48:49]
	s_waitcnt vmcnt(0)
	v_lshlrev_b32_e32 v190, 16, v186
	v_and_b32_e32 v191, 0xffff0000, v186
	v_lshlrev_b32_e32 v186, 16, v187
	v_and_b32_e32 v187, 0xffff0000, v187
	v_lshlrev_b32_e32 v194, 16, v188
	v_and_b32_e32 v195, 0xffff0000, v188
	v_lshlrev_b32_e32 v188, 16, v189
	v_and_b32_e32 v189, 0xffff0000, v189
	v_pk_add_f32 v[126:127], v[126:127], v[186:187]
	v_pk_add_f32 v[124:125], v[124:125], v[190:191]
	v_pk_add_f32 v[122:123], v[122:123], v[188:189]
	v_pk_add_f32 v[120:121], v[120:121], v[194:195]
	s_cbranch_vccnz .LBB0_149
	global_store_dwordx4 v[180:181], v[124:127], off
	global_store_dwordx4 v[180:181], v[120:123], off offset:16
	v_lshl_add_u64 v[178:179], v[178:179], 1, v[166:167]
	s_cbranch_execnz .LBB0_69

; template <class Epi, class Sched, bool ALIGN_EPI = false, bool SP2 = false>
; __device__ __forceinline__ void gemm_phase(PG8_LAS unsigned char* lds, const Gemm g, const Sched& S, const Epi& E) {
;     ...
;         for (int t = 0; t < nt; t += 2) {
;             const bool last = (t == nt - 2);
;             const char* a1 = cA + (size_t)(t + 1) * kstep;
;             const char* a2 = last ? nA : cA + (size_t)(t + 2) * kstep; const char* b2 = last ? nB : cB + (size_t)(t + 2) * kstep;
.Lnb3_g2:
	s_setprio 0
	s_add_i32 s76, s76, 2
	s_add_u32 s56, s56, 0x100
	s_addc_u32 s57, s57, 0
	s_add_u32 s49, s49, 0x100
	s_addc_u32 s51, s51, 0
	s_cmp_gt_u32 s76, 13
; __device__ __forceinline__ float row_rstd(const float* ssp, int row, int fq) {
;     const f32x4 t = *((const f32x4*)(ssp + (size_t)row * 16) + fq); float s = (t[0] + t[1]) + (t[2] + t[3]); s += __shfl_xor(s, 16); s += __shfl_xor(s, 32); return rsqrtf(s * (1.0f / DM) + EPS); }
;     __device__ __forceinline__ void operator()(const f32x4 (&acc)[2][2][4][2], const Unit& u, int wr, int wc, int fr, int fq) const {
;         const int T = u.pn; const int row0 = u.pm * BM + wr * 64 + fr;
;         unsigned char* const chb = ws + WS_SLAB + (size_t)(u.pm >> 4) * SLAB; const int lrow0 = row0 & (SEQ - 1);
;         bf16_t* const Q = (bf16_t*)(chb + SL_Q); bf16_t* const K = (bf16_t*)(chb + SL_K); bf16_t* const Vt = (bf16_t*)(chb + SL_V); bf16_t* const GLU = (bf16_t*)(chb + SL_GLU);
;         bf16_t* const P = (bf16_t*)(chb + SL_P); bf16_t* const BG = (bf16_t*)(ws + WS_HCBG) + 512;
;         float rx[2][4];
; #pragma unroll
;         for (int ai = 0; ai < 2; ++ai)
; #pragma unroll
;             for (int m = 0; m < 4; ++m) rx[ai][m] = row_rstd(ssp, row0 + ai * HALF + m * 16, fq);
;         if (T < 4) {
.LBB0_203:
	v_and_b32_e32 v129, 64, v229
	v_xor_b32_e32 v128, 16, v229
	v_add_u32_e32 v129, 64, v129
	v_cmp_lt_i32_e32 vcc, v128, v129
	v_lshl_add_u32 v132, s42, 8, v153
	v_ashrrev_i32_e32 v133, 31, v132
	v_cndmask_b32_e32 v128, v229, v128, vcc
	v_lshlrev_b32_e32 v169, 2, v128
	v_xor_b32_e32 v128, 32, v229
	v_cmp_lt_i32_e32 vcc, v128, v129
	s_mov_b32 s4, 0x358637bd
	v_mov_b64_e32 v[140:141], s[4:5]
	v_cndmask_b32_e32 v128, v229, v128, vcc
	v_lshlrev_b32_e32 v167, 2, v128
	v_lshlrev_b64 v[128:129], 6, v[132:133]
	v_lshl_add_u64 v[128:129], v[154:155], 0, v[128:129]
	global_load_dwordx4 v[186:189], v[128:129], off
	global_load_dwordx4 v[194:197], v[128:129], off offset:1024
	global_load_dwordx4 v[198:201], v[128:129], off offset:2048
	global_load_dwordx4 v[202:205], v[128:129], off offset:3072
	v_add_co_u32_e32 v184, vcc, 0x2000, v128
	s_nop 1
	v_addc_co_u32_e32 v185, vcc, 0, v129, vcc
	global_load_dwordx4 v[206:209], v[184:185], off
	global_load_dwordx4 v[210:213], v[184:185], off offset:1024
	global_load_dwordx4 v[214:217], v[184:185], off offset:2048
	global_load_dwordx4 v[218:221], v[184:185], off offset:3072
	s_ashr_i32 s19, s42, 4
	v_add_u32_e32 v178, 0x90, v132
	v_ashrrev_i32_e32 v179, 31, v178
	v_add_u32_e32 v180, 0xa0, v132
	v_ashrrev_i32_e32 v181, 31, v180
	v_add_u32_e32 v182, 0xb0, v132
	v_ashrrev_i32_e32 v183, 31, v182
	s_mul_hi_i32 s18, s19, 0x1c00000
	s_mul_i32 s19, s19, 0x1c00000
	s_add_u32 s49, s72, s19
	s_addc_u32 s51, s73, s18
	v_and_b32_e32 v171, 0xfcf, v132
	s_cmp_gt_i32 s75, 3
	s_waitcnt vmcnt(7)
	v_mov_b32_e32 v134, v187
	v_mov_b32_e32 v135, v188
	v_mov_b32_e32 v187, v189
	v_pk_add_f32 v[136:137], v[134:135], v[186:187]
	v_or_b32_e32 v134, 16, v132
	v_ashrrev_i32_e32 v135, 31, v134
	s_waitcnt vmcnt(6)
	v_mov_b32_e32 v138, v195
	v_mov_b32_e32 v139, v196
	v_mov_b32_e32 v195, v197
	v_pk_add_f32 v[128:129], v[138:139], v[194:195]
	v_mov_b32_e32 v131, v136
	v_mov_b32_e32 v130, v128
	v_mov_b32_e32 v136, v129
	v_pk_add_f32 v[128:129], v[130:131], v[136:137]
	ds_bpermute_b32 v131, v169, v129
	ds_bpermute_b32 v130, v169, v128
	v_or_b32_e32 v138, 32, v132
	v_ashrrev_i32_e32 v139, 31, v138
	s_waitcnt lgkmcnt(0)
	v_pk_add_f32 v[128:129], v[128:129], v[130:131]
	ds_bpermute_b32 v131, v167, v129
	ds_bpermute_b32 v130, v167, v128
	s_waitcnt lgkmcnt(0)
	v_pk_add_f32 v[128:129], v[128:129], v[130:131]
	s_nop 0
	v_pk_fma_f32 v[128:129], v[128:129], s[38:39], v[140:141] op_sel_hi:[1,0,0]
	s_nop 0
	v_mul_f32_e32 v130, 0x4b800000, v129
	v_cmp_gt_f32_e64 s[42:43], s99, v129
	v_cmp_gt_f32_e32 vcc, s99, v128
	s_nop 0
	v_cndmask_b32_e64 v129, v129, v130, s[42:43]
	v_rsq_f32_e32 v129, v129
	s_nop 0
	v_mul_f32_e32 v130, 0x45800000, v129
	v_cndmask_b32_e64 v170, v129, v130, s[42:43]
	v_mul_f32_e32 v129, 0x4b800000, v128
	v_cndmask_b32_e32 v128, v128, v129, vcc
	v_rsq_f32_e32 v128, v128
	s_nop 0
	v_mul_f32_e32 v129, 0x45800000, v128
	v_cndmask_b32_e32 v166, v128, v129, vcc
	s_waitcnt vmcnt(5)
	v_mov_b32_e32 v136, v199
	v_mov_b32_e32 v137, v200
	v_mov_b32_e32 v199, v201
	v_pk_add_f32 v[142:143], v[136:137], v[198:199]
	v_or_b32_e32 v136, 48, v132
	v_ashrrev_i32_e32 v137, 31, v136
	s_waitcnt vmcnt(4)
	v_mov_b32_e32 v172, v203
	v_mov_b32_e32 v173, v204
	v_mov_b32_e32 v203, v205
	v_pk_add_f32 v[128:129], v[172:173], v[202:203]
	v_mov_b32_e32 v131, v142
	v_mov_b32_e32 v130, v128
	v_mov_b32_e32 v142, v129
	v_pk_add_f32 v[128:129], v[130:131], v[142:143]
	ds_bpermute_b32 v131, v169, v129
	ds_bpermute_b32 v130, v169, v128
	v_add_u32_e32 v142, 0x80, v132
	v_ashrrev_i32_e32 v143, 31, v142
	s_waitcnt lgkmcnt(0)
	v_pk_add_f32 v[128:129], v[128:129], v[130:131]
	ds_bpermute_b32 v131, v167, v129
	ds_bpermute_b32 v130, v167, v128
	s_waitcnt lgkmcnt(0)
	v_pk_add_f32 v[128:129], v[128:129], v[130:131]
	s_nop 0
	v_pk_fma_f32 v[128:129], v[128:129], s[38:39], v[140:141] op_sel_hi:[1,0,0]
	s_nop 0
	v_mul_f32_e32 v130, 0x4b800000, v129
	v_cmp_gt_f32_e64 s[42:43], s99, v129
	v_cmp_gt_f32_e32 vcc, s99, v128
	s_nop 0
	v_cndmask_b32_e64 v129, v129, v130, s[42:43]
	v_rsq_f32_e32 v129, v129
	s_nop 0
	v_mul_f32_e32 v130, 0x45800000, v129
	v_cndmask_b32_e64 v172, v129, v130, s[42:43]
	v_mul_f32_e32 v129, 0x4b800000, v128
	v_cndmask_b32_e32 v128, v128, v129, vcc
	v_rsq_f32_e32 v128, v128
	s_nop 0
	v_mul_f32_e32 v129, 0x45800000, v128
	v_cndmask_b32_e32 v164, v128, v129, vcc
	s_waitcnt vmcnt(3)
	v_mov_b32_e32 v174, v207
	v_mov_b32_e32 v175, v208
	v_mov_b32_e32 v207, v209
	v_pk_add_f32 v[174:175], v[174:175], v[206:207]
	s_waitcnt vmcnt(2)
	v_mov_b32_e32 v176, v211
	v_mov_b32_e32 v177, v212
	v_mov_b32_e32 v211, v213
	v_pk_add_f32 v[128:129], v[176:177], v[210:211]
	v_mov_b32_e32 v131, v174
	v_mov_b32_e32 v130, v128
	v_mov_b32_e32 v174, v129
	v_pk_add_f32 v[128:129], v[130:131], v[174:175]
	ds_bpermute_b32 v131, v169, v129
	ds_bpermute_b32 v130, v169, v128
	s_waitcnt lgkmcnt(0)
	v_pk_add_f32 v[128:129], v[128:129], v[130:131]
	ds_bpermute_b32 v131, v167, v129
	ds_bpermute_b32 v130, v167, v128
	s_waitcnt lgkmcnt(0)
	v_pk_add_f32 v[128:129], v[128:129], v[130:131]
	s_nop 0
	v_pk_fma_f32 v[128:129], v[128:129], s[38:39], v[140:141] op_sel_hi:[1,0,0]
	s_nop 0
	v_mul_f32_e32 v130, 0x4b800000, v129
	v_cmp_gt_f32_e64 s[42:43], s99, v129
	v_cmp_gt_f32_e32 vcc, s99, v128
	s_nop 0
	v_cndmask_b32_e64 v129, v129, v130, s[42:43]
	v_rsq_f32_e32 v129, v129
	s_nop 0
	v_mul_f32_e32 v130, 0x45800000, v129
	v_cndmask_b32_e64 v168, v129, v130, s[42:43]
	v_mul_f32_e32 v129, 0x4b800000, v128
	v_cndmask_b32_e32 v128, v128, v129, vcc
	v_rsq_f32_e32 v128, v128
	s_nop 0
	v_mul_f32_e32 v129, 0x45800000, v128
	v_cndmask_b32_e32 v162, v128, v129, vcc
	s_waitcnt vmcnt(1)
	v_mov_b32_e32 v174, v215
	v_mov_b32_e32 v175, v216
	v_mov_b32_e32 v215, v217
	v_pk_add_f32 v[174:175], v[174:175], v[214:215]
	s_waitcnt vmcnt(0)
	v_mov_b32_e32 v176, v219
	v_mov_b32_e32 v177, v220
	v_mov_b32_e32 v219, v221
	v_pk_add_f32 v[128:129], v[176:177], v[218:219]
	v_mov_b32_e32 v131, v174
	v_mov_b32_e32 v130, v128
	v_mov_b32_e32 v174, v129
	v_pk_add_f32 v[128:129], v[130:131], v[174:175]
	ds_bpermute_b32 v131, v169, v129
	ds_bpermute_b32 v130, v169, v128
	s_waitcnt lgkmcnt(0)
	v_pk_add_f32 v[128:129], v[128:129], v[130:131]
	ds_bpermute_b32 v131, v167, v129
	ds_bpermute_b32 v130, v167, v128
	s_waitcnt lgkmcnt(0)
	v_pk_add_f32 v[128:129], v[128:129], v[130:131]
	s_nop 0
	v_pk_fma_f32 v[128:129], v[128:129], s[38:39], v[140:141] op_sel_hi:[1,0,0]
	s_nop 0
	v_mul_f32_e32 v130, 0x4b800000, v129
	v_cmp_gt_f32_e64 s[42:43], s99, v129
	v_cmp_gt_f32_e32 vcc, s99, v128
	s_nop 0
	v_cndmask_b32_e64 v129, v129, v130, s[42:43]
	v_rsq_f32_e32 v129, v129
	s_nop 0
	v_mul_f32_e32 v130, 0x45800000, v129
	v_cndmask_b32_e64 v176, v129, v130, s[42:43]
	v_mul_f32_e32 v129, 0x4b800000, v128
	v_cndmask_b32_e32 v128, v128, v129, vcc
	v_rsq_f32_e32 v128, v128
	s_mov_b64 s[42:43], -1
	v_mul_f32_e32 v129, 0x45800000, v128
	v_cndmask_b32_e32 v174, v128, v129, vcc
	s_cbranch_scc1 .LBB0_206
	s_andn2_b64 vcc, exec, s[42:43]
	s_cbranch_vccz .LBB0_215

;     __device__ __forceinline__ void operator()(const f32x4 (&acc)[2][2][4][2], const Unit& u, int wr, int wc, int fr, int fq) const {
;         const int br = u.kind / 3, part = u.kind % 3;
;         unsigned voff = (unsigned)((wr * 4 + wc) * 64 + fq * 16 + fr) * 16u; asm volatile("" : "+v"(voff));
;         unsigned char* const tmpb = ws + WS_SLAB + (size_t)(tslot >> 5) * SLAB + SL_TMP + (size_t)(tslot & 31) * 131072;
;         const int row0 = u.pm * BM + wr * 64 + fr, col0 = u.pn * BM + 32 * wc + 8 * fq;
;         if (part == 1) {
;             float rx[2][4];
; #pragma unroll
;             for (int ai = 0; ai < 2; ++ai)
; #pragma unroll
;                 for (int m = 0; m < 4; ++m) rx[ai][m] = row_rstd(ssp, row0 + ai * HALF + m * 16, fq);
; #pragma unroll
;             for (int bj = 0; bj < 2; ++bj) {
;                 const f32x4 bv0 = *(const f32x4*)(gb + br * 1024 + col0 + 128 * bj), bv1 = *(const f32x4*)(gb + br * 1024 + col0 + 128 * bj + 4);
; #pragma unroll
;                 for (int ai = 0; ai < 2; ++ai)
; #pragma unroll
;                     for (int m = 0; m < 4; ++m) {
;                         const f32x4 a0 = acc[ai][bj][m][0] * rx[ai][m] + bv0, a1 = acc[ai][bj][m][1] * rx[ai][m] + bv1; f32x4 o0, o1;
; #pragma unroll
;                         for (int e = 0; e < 4; ++e) { o0[e] = sigm(a0[e]); o1[e] = sigm(a1[e]); }
;                         *(u32x4*)(tmpb + ((ai * 4 + m) * 2 + bj) * 8192 + voff) = pack8(o0, o1); }
;                 asm volatile("" ::: "memory"); }
;         } else {
;             bf16_t* const MRG = (bf16_t*)(ws + WS_SLAB + (size_t)(u.pm >> 4) * SLAB + SL_MRG); const int lrow0 = row0 & (SEQ - 1);
; #pragma unroll
;             for (int ai = 0; ai < 2; ++ai) {
;                 u32x4 gw[4][2], pw[4][2];
; #pragma unroll
;                 for (int m = 0; m < 4; ++m)
; #pragma unroll
;                     for (int bj = 0; bj < 2; ++bj) { gw[m][bj] = *(const u32x4*)(tmpb + ((ai * 4 + m) * 2 + bj) * 8192 + voff);
;                         if (br > 0) pw[m][bj] = *(const u32x4*)(MRG + (size_t)(lrow0 + ai * HALF + m * 16) * 1024 + col0 + 128 * bj); }
; #pragma unroll
;                 for (int m = 0; m < 4; ++m)
; #pragma unroll
;                     for (int bj = 0; bj < 2; ++bj) { f32x4 g0, g1; unpack8(gw[m][bj], g0, g1);
;                         f32x4 v0 = acc[ai][bj][m][0] * g0, v1 = acc[ai][bj][m][1] * g1;
.Lnb3_g3:
	s_setprio 0
	s_add_i32 s76, s76, 2
	s_add_u32 s34, s34, 0x100
	s_addc_u32 s35, s35, 0
	s_add_u32 s19, s19, 0x100
	s_addc_u32 s75, s75, 0
	s_cmp_gt_u32 s76, 5
.LBB0_491:
	s_mul_i32 s10, s43, 0xab
	s_bfe_u32 s52, s10, 0x70009
	s_mul_i32 s10, s52, 3
	s_sub_i32 s10, s43, s10
	s_and_b32 s19, s10, 0xff
	s_cmp_lg_u32 s19, 0
	s_cselect_b64 s[34:35], -1, 0
	s_cmp_eq_u32 s19, 0
	s_cbranch_scc1 .LBB0_560
	v_mov_b32_e32 v192, v248
	v_lshl_add_u32 v210, s42, 8, v245
	v_lshl_or_b32 v208, s18, 8, v247
	s_cmp_lg_u32 s19, 1
	s_mov_b64 s[18:19], -1
	s_cbranch_scc0 .LBB0_558
	s_ashr_i32 s10, s42, 4
	s_mul_hi_i32 s11, s10, 0x1c00000
	s_mul_i32 s10, s10, 0x1c00000
	s_add_u32 s10, s71, s10
	s_addc_u32 s11, s72, s11
	v_lshlrev_b32_e32 v128, 1, v208
	v_mov_b32_e32 v129, v193
	v_lshlrev_b32_e32 v130, 11, v210
	s_cmp_gt_u32 s43, 2
	v_lshl_add_u64 v[128:129], s[10:11], 0, v[128:129]
	v_and_b32_e32 v130, 0x7e7800, v130
	v_mov_b32_e32 v131, v193
	s_cselect_b64 s[50:51], -1, 0
	v_lshl_add_u64 v[212:213], v[128:129], 0, v[130:131]
	v_lshl_add_u64 v[214:215], s[30:31], 0, v[192:193]
	v_and_b32_e32 v128, 8, v229
	v_mov_b32_e32 v129, 0xffffc040
	v_mov_b32_e32 v131, 0x4040
	v_cmp_ne_u32_e64 s[42:43], 0, v128
	s_nop 1
	v_cndmask_b32_e64 v232, 0, v129, s[42:43]
	v_cndmask_b32_e64 v234, v131, 0, s[42:43]
	v_ashrrev_i32_e32 v233, 31, v232
	v_mov_b32_e32 v235, v193
	v_lshl_add_u64 v[252:253], v[212:213], 0, v[234:235]
	v_lshl_add_u64 v[212:213], v[212:213], 0, v[232:233]
	s_and_b64 vcc, exec, s[50:51]
	s_cbranch_vccnz .Le2_rmw
	global_load_dwordx4 v[128:131], v[214:215], off
	s_mov_b64 s[10:11], 0x2000
	v_lshl_add_u64 v[224:225], v[214:215], 0, s[10:11]
	global_load_dwordx4 v[132:135], v[224:225], off
	s_mov_b64 s[10:11], 0x4000
	v_lshl_add_u64 v[224:225], v[214:215], 0, s[10:11]
	global_load_dwordx4 v[136:139], v[224:225], off
	s_mov_b64 s[10:11], 0x6000
	v_lshl_add_u64 v[224:225], v[214:215], 0, s[10:11]
	global_load_dwordx4 v[140:143], v[224:225], off
	s_mov_b64 s[10:11], 0x8000
	v_lshl_add_u64 v[224:225], v[214:215], 0, s[10:11]
	global_load_dwordx4 v[144:147], v[224:225], off
	s_mov_b64 s[10:11], 0xa000
	v_lshl_add_u64 v[224:225], v[214:215], 0, s[10:11]
	global_load_dwordx4 v[148:151], v[224:225], off
	s_mov_b64 s[10:11], 0xc000
	v_lshl_add_u64 v[224:225], v[214:215], 0, s[10:11]
	global_load_dwordx4 v[152:155], v[224:225], off
	s_mov_b64 s[10:11], 0xe000
	v_lshl_add_u64 v[224:225], v[214:215], 0, s[10:11]
	global_load_dwordx4 v[156:159], v[224:225], off
	s_waitcnt vmcnt(7)
	v_lshlrev_b32_e32 v216, 16, v128
	v_and_b32_e32 v217, 0xffff0000, v128
	v_lshlrev_b32_e32 v218, 16, v129
	v_and_b32_e32 v219, 0xffff0000, v129
	v_lshlrev_b32_e32 v220, 16, v130
	v_and_b32_e32 v221, 0xffff0000, v130
	v_lshlrev_b32_e32 v222, 16, v131
	v_and_b32_e32 v223, 0xffff0000, v131
	v_pk_mul_f32 v[124:125], v[124:125], v[216:217]
	v_pk_mul_f32 v[126:127], v[126:127], v[218:219]
	v_pk_mul_f32 v[120:121], v[120:121], v[220:221]
	v_pk_mul_f32 v[122:123], v[122:123], v[222:223]
	v_cvt_pk_bf16_f32 v128, v124, v125
	v_cvt_pk_bf16_f32 v129, v126, v127
	v_cvt_pk_bf16_f32 v130, v120, v121
	v_cvt_pk_bf16_f32 v131, v122, v123
	s_waitcnt vmcnt(6)
	v_lshlrev_b32_e32 v216, 16, v132
	v_and_b32_e32 v217, 0xffff0000, v132
	v_lshlrev_b32_e32 v218, 16, v133
	v_and_b32_e32 v219, 0xffff0000, v133
	v_lshlrev_b32_e32 v220, 16, v134
	v_and_b32_e32 v221, 0xffff0000, v134
	v_lshlrev_b32_e32 v222, 16, v135
	v_and_b32_e32 v223, 0xffff0000, v135
	v_pk_mul_f32 v[92:93], v[92:93], v[216:217]
	v_pk_mul_f32 v[94:95], v[94:95], v[218:219]
	v_pk_mul_f32 v[88:89], v[88:89], v[220:221]
	v_pk_mul_f32 v[90:91], v[90:91], v[222:223]
	v_cvt_pk_bf16_f32 v132, v92, v93
	v_cvt_pk_bf16_f32 v133, v94, v95
	v_cvt_pk_bf16_f32 v134, v88, v89
	v_cvt_pk_bf16_f32 v135, v90, v91
	s_waitcnt vmcnt(5)
	v_lshlrev_b32_e32 v216, 16, v136
	v_and_b32_e32 v217, 0xffff0000, v136
	v_lshlrev_b32_e32 v218, 16, v137
	v_and_b32_e32 v219, 0xffff0000, v137
	v_lshlrev_b32_e32 v220, 16, v138
	v_and_b32_e32 v221, 0xffff0000, v138
	v_lshlrev_b32_e32 v222, 16, v139
	v_and_b32_e32 v223, 0xffff0000, v139
	v_pk_mul_f32 v[116:117], v[116:117], v[216:217]
	v_pk_mul_f32 v[118:119], v[118:119], v[218:219]
	v_pk_mul_f32 v[112:113], v[112:113], v[220:221]
	v_pk_mul_f32 v[114:115], v[114:115], v[222:223]
	v_cvt_pk_bf16_f32 v136, v116, v117
	v_cvt_pk_bf16_f32 v137, v118, v119
	v_cvt_pk_bf16_f32 v138, v112, v113
	v_cvt_pk_bf16_f32 v139, v114, v115
	s_waitcnt vmcnt(4)
; __device__ __forceinline__ u32x4 pack8(const f32x4& a, const f32x4& b) { u32x4 w; w.x = pk2(a[0], a[1]); w.y = pk2(a[2], a[3]); w.z = pk2(b[0], b[1]); w.w = pk2(b[2], b[3]); return w; }
; __device__ __forceinline__ void unpack8(const u32x4& w, f32x4& a, f32x4& b) { a[0] = bflo(w.x); a[1] = bfhi(w.x); a[2] = bflo(w.y); a[3] = bfhi(w.y); b[0] = bflo(w.z); b[1] = bfhi(w.z); b[2] = bflo(w.w); b[3] = bfhi(w.w); }
;     __device__ __forceinline__ void operator()(const f32x4 (&acc)[2][2][4][2], const Unit& u, int wr, int wc, int fr, int fq) const {
;     ...
;                     for (int bj = 0; bj < 2; ++bj) { gw[m][bj] = *(const u32x4*)(tmpb + ((ai * 4 + m) * 2 + bj) * 8192 + voff);
;                         if (br > 0) pw[m][bj] = *(const u32x4*)(MRG + (size_t)(lrow0 + ai * HALF + m * 16) * 1024 + col0 + 128 * bj); }
; #pragma unroll
;                 for (int m = 0; m < 4; ++m)
; #pragma unroll
;                     for (int bj = 0; bj < 2; ++bj) { f32x4 g0, g1; unpack8(gw[m][bj], g0, g1);
;                         f32x4 v0 = acc[ai][bj][m][0] * g0, v1 = acc[ai][bj][m][1] * g1;
;                         if (br > 0) { f32x4 p0, p1; unpack8(pw[m][bj], p0, p1); v0 += p0; v1 += p1; }
;                         *(u32x4*)(MRG + (size_t)(lrow0 + ai * HALF + m * 16) * 1024 + col0 + 128 * bj) = pack8(v0, v1); }
	v_lshlrev_b32_e32 v216, 16, v140
	v_and_b32_e32 v217, 0xffff0000, v140
	v_lshlrev_b32_e32 v218, 16, v141
	v_and_b32_e32 v219, 0xffff0000, v141
	v_lshlrev_b32_e32 v220, 16, v142
	v_and_b32_e32 v221, 0xffff0000, v142
	v_lshlrev_b32_e32 v222, 16, v143
	v_and_b32_e32 v223, 0xffff0000, v143
	v_pk_mul_f32 v[84:85], v[84:85], v[216:217]
	v_pk_mul_f32 v[86:87], v[86:87], v[218:219]
	v_pk_mul_f32 v[80:81], v[80:81], v[220:221]
	v_pk_mul_f32 v[82:83], v[82:83], v[222:223]
	v_cvt_pk_bf16_f32 v140, v84, v85
	v_cvt_pk_bf16_f32 v141, v86, v87
	v_cvt_pk_bf16_f32 v142, v80, v81
	v_cvt_pk_bf16_f32 v143, v82, v83
	s_mov_b64 s[10:11], 0x10000
	v_lshl_add_u64 v[224:225], v[214:215], 0, s[10:11]
	global_load_dwordx4 v[124:127], v[224:225], off
	s_mov_b64 s[10:11], 0x12000
	v_lshl_add_u64 v[224:225], v[214:215], 0, s[10:11]
	global_load_dwordx4 v[92:95], v[224:225], off
	s_mov_b64 s[10:11], 0x14000
	v_lshl_add_u64 v[224:225], v[214:215], 0, s[10:11]
	global_load_dwordx4 v[116:119], v[224:225], off
	s_mov_b64 s[10:11], 0x16000
	v_lshl_add_u64 v[224:225], v[214:215], 0, s[10:11]
	global_load_dwordx4 v[84:87], v[224:225], off
	v_mov_b32_dpp v232, v132 row_ror:8 row_mask:0xf bank_mask:0xf
	v_mov_b32_dpp v233, v133 row_ror:8 row_mask:0xf bank_mask:0xf
	v_mov_b32_dpp v234, v134 row_ror:8 row_mask:0xf bank_mask:0xf
	v_mov_b32_dpp v235, v135 row_ror:8 row_mask:0xf bank_mask:0xf
	v_cndmask_b32_e64 v132, v128, v232, s[42:43]
	v_cndmask_b32_e64 v133, v129, v233, s[42:43]
	v_cndmask_b32_e64 v134, v130, v234, s[42:43]
	v_cndmask_b32_e64 v135, v131, v235, s[42:43]
	v_cndmask_b32_e64 v232, v232, v128, s[42:43]
	v_cndmask_b32_e64 v233, v233, v129, s[42:43]
	v_cndmask_b32_e64 v234, v234, v130, s[42:43]
	v_cndmask_b32_e64 v235, v235, v131, s[42:43]
	global_store_dwordx4 v[212:213], v[132:135], off
	global_store_dwordx4 v[252:253], v[232:235], off
	s_mov_b64 s[10:11], 0x8000
	v_lshl_add_u64 v[224:225], v[212:213], 0, s[10:11]
	s_mov_b64 s[10:11], 0x8000
	v_lshl_add_u64 v[250:251], v[252:253], 0, s[10:11]
	v_mov_b32_dpp v232, v140 row_ror:8 row_mask:0xf bank_mask:0xf
	v_mov_b32_dpp v233, v141 row_ror:8 row_mask:0xf bank_mask:0xf
	v_mov_b32_dpp v234, v142 row_ror:8 row_mask:0xf bank_mask:0xf
	v_mov_b32_dpp v235, v143 row_ror:8 row_mask:0xf bank_mask:0xf
	v_cndmask_b32_e64 v140, v136, v232, s[42:43]
	v_cndmask_b32_e64 v141, v137, v233, s[42:43]
	v_cndmask_b32_e64 v142, v138, v234, s[42:43]
	v_cndmask_b32_e64 v143, v139, v235, s[42:43]
	v_cndmask_b32_e64 v232, v232, v136, s[42:43]
	v_cndmask_b32_e64 v233, v233, v137, s[42:43]
	v_cndmask_b32_e64 v234, v234, v138, s[42:43]
	v_cndmask_b32_e64 v235, v235, v139, s[42:43]
	global_store_dwordx4 v[224:225], v[140:143], off
	global_store_dwordx4 v[250:251], v[232:235], off
	s_nop 1
	s_waitcnt vmcnt(11)
	v_lshlrev_b32_e32 v216, 16, v144
	v_and_b32_e32 v217, 0xffff0000, v144
	v_lshlrev_b32_e32 v218, 16, v145
	v_and_b32_e32 v219, 0xffff0000, v145
	v_lshlrev_b32_e32 v220, 16, v146
	v_and_b32_e32 v221, 0xffff0000, v146
	v_lshlrev_b32_e32 v222, 16, v147
	v_and_b32_e32 v223, 0xffff0000, v147
	v_pk_mul_f32 v[108:109], v[108:109], v[216:217]
	v_pk_mul_f32 v[110:111], v[110:111], v[218:219]
	v_pk_mul_f32 v[104:105], v[104:105], v[220:221]
	v_pk_mul_f32 v[106:107], v[106:107], v[222:223]
	v_cvt_pk_bf16_f32 v144, v108, v109
	v_cvt_pk_bf16_f32 v145, v110, v111
	v_cvt_pk_bf16_f32 v146, v104, v105
	v_cvt_pk_bf16_f32 v147, v106, v107
	s_waitcnt vmcnt(10)
	v_lshlrev_b32_e32 v216, 16, v148
	v_and_b32_e32 v217, 0xffff0000, v148
	v_lshlrev_b32_e32 v218, 16, v149
	v_and_b32_e32 v219, 0xffff0000, v149
	v_lshlrev_b32_e32 v220, 16, v150
	v_and_b32_e32 v221, 0xffff0000, v150
	v_lshlrev_b32_e32 v222, 16, v151
	v_and_b32_e32 v223, 0xffff0000, v151
	v_pk_mul_f32 v[76:77], v[76:77], v[216:217]
	v_pk_mul_f32 v[78:79], v[78:79], v[218:219]
	v_pk_mul_f32 v[72:73], v[72:73], v[220:221]
	v_pk_mul_f32 v[74:75], v[74:75], v[222:223]
	v_cvt_pk_bf16_f32 v148, v76, v77
	v_cvt_pk_bf16_f32 v149, v78, v79
	v_cvt_pk_bf16_f32 v150, v72, v73
	v_cvt_pk_bf16_f32 v151, v74, v75
	s_waitcnt vmcnt(9)
	v_lshlrev_b32_e32 v216, 16, v152
	v_and_b32_e32 v217, 0xffff0000, v152
	v_lshlrev_b32_e32 v218, 16, v153
	v_and_b32_e32 v219, 0xffff0000, v153
	v_lshlrev_b32_e32 v220, 16, v154
	v_and_b32_e32 v221, 0xffff0000, v154
	v_lshlrev_b32_e32 v222, 16, v155
	v_and_b32_e32 v223, 0xffff0000, v155
	v_pk_mul_f32 v[100:101], v[100:101], v[216:217]
	v_pk_mul_f32 v[102:103], v[102:103], v[218:219]
	v_pk_mul_f32 v[96:97], v[96:97], v[220:221]
	v_pk_mul_f32 v[98:99], v[98:99], v[222:223]
	v_cvt_pk_bf16_f32 v152, v100, v101
	v_cvt_pk_bf16_f32 v153, v102, v103
	v_cvt_pk_bf16_f32 v154, v96, v97
	v_cvt_pk_bf16_f32 v155, v98, v99
	s_waitcnt vmcnt(8)
; __device__ __forceinline__ u32x4 pack8(const f32x4& a, const f32x4& b) { u32x4 w; w.x = pk2(a[0], a[1]); w.y = pk2(a[2], a[3]); w.z = pk2(b[0], b[1]); w.w = pk2(b[2], b[3]); return w; }
; __device__ __forceinline__ void unpack8(const u32x4& w, f32x4& a, f32x4& b) { a[0] = bflo(w.x); a[1] = bfhi(w.x); a[2] = bflo(w.y); a[3] = bfhi(w.y); b[0] = bflo(w.z); b[1] = bfhi(w.z); b[2] = bflo(w.w); b[3] = bfhi(w.w); }
;     __device__ __forceinline__ void operator()(const f32x4 (&acc)[2][2][4][2], const Unit& u, int wr, int wc, int fr, int fq) const {
;     ...
;                     for (int bj = 0; bj < 2; ++bj) { gw[m][bj] = *(const u32x4*)(tmpb + ((ai * 4 + m) * 2 + bj) * 8192 + voff);
;                         if (br > 0) pw[m][bj] = *(const u32x4*)(MRG + (size_t)(lrow0 + ai * HALF + m * 16) * 1024 + col0 + 128 * bj); }
; #pragma unroll
;                 for (int m = 0; m < 4; ++m)
; #pragma unroll
;                     for (int bj = 0; bj < 2; ++bj) { f32x4 g0, g1; unpack8(gw[m][bj], g0, g1);
;                         f32x4 v0 = acc[ai][bj][m][0] * g0, v1 = acc[ai][bj][m][1] * g1;
;                         if (br > 0) { f32x4 p0, p1; unpack8(pw[m][bj], p0, p1); v0 += p0; v1 += p1; }
;                         *(u32x4*)(MRG + (size_t)(lrow0 + ai * HALF + m * 16) * 1024 + col0 + 128 * bj) = pack8(v0, v1); }
	v_lshlrev_b32_e32 v216, 16, v156
	v_and_b32_e32 v217, 0xffff0000, v156
	v_lshlrev_b32_e32 v218, 16, v157
	v_and_b32_e32 v219, 0xffff0000, v157
	v_lshlrev_b32_e32 v220, 16, v158
	v_and_b32_e32 v221, 0xffff0000, v158
	v_lshlrev_b32_e32 v222, 16, v159
	v_and_b32_e32 v223, 0xffff0000, v159
	v_pk_mul_f32 v[68:69], v[68:69], v[216:217]
	v_pk_mul_f32 v[70:71], v[70:71], v[218:219]
	v_pk_mul_f32 v[64:65], v[64:65], v[220:221]
	v_pk_mul_f32 v[66:67], v[66:67], v[222:223]
	v_cvt_pk_bf16_f32 v156, v68, v69
	v_cvt_pk_bf16_f32 v157, v70, v71
	v_cvt_pk_bf16_f32 v158, v64, v65
	v_cvt_pk_bf16_f32 v159, v66, v67
	s_mov_b64 s[10:11], 0x18000
	v_lshl_add_u64 v[224:225], v[214:215], 0, s[10:11]
	global_load_dwordx4 v[108:111], v[224:225], off
	s_mov_b64 s[10:11], 0x1a000
	v_lshl_add_u64 v[224:225], v[214:215], 0, s[10:11]
	global_load_dwordx4 v[76:79], v[224:225], off
	s_mov_b64 s[10:11], 0x1c000
	v_lshl_add_u64 v[224:225], v[214:215], 0, s[10:11]
	global_load_dwordx4 v[100:103], v[224:225], off
	s_mov_b64 s[10:11], 0x1e000
	v_lshl_add_u64 v[224:225], v[214:215], 0, s[10:11]
	global_load_dwordx4 v[68:71], v[224:225], off
	s_mov_b64 s[10:11], 0x10000
	v_lshl_add_u64 v[224:225], v[212:213], 0, s[10:11]
	s_mov_b64 s[10:11], 0x10000
	v_lshl_add_u64 v[250:251], v[252:253], 0, s[10:11]
	v_mov_b32_dpp v232, v148 row_ror:8 row_mask:0xf bank_mask:0xf
	v_mov_b32_dpp v233, v149 row_ror:8 row_mask:0xf bank_mask:0xf
	v_mov_b32_dpp v234, v150 row_ror:8 row_mask:0xf bank_mask:0xf
	v_mov_b32_dpp v235, v151 row_ror:8 row_mask:0xf bank_mask:0xf
	v_cndmask_b32_e64 v148, v144, v232, s[42:43]
	v_cndmask_b32_e64 v149, v145, v233, s[42:43]
	v_cndmask_b32_e64 v150, v146, v234, s[42:43]
	v_cndmask_b32_e64 v151, v147, v235, s[42:43]
	v_cndmask_b32_e64 v232, v232, v144, s[42:43]
	v_cndmask_b32_e64 v233, v233, v145, s[42:43]
	v_cndmask_b32_e64 v234, v234, v146, s[42:43]
	v_cndmask_b32_e64 v235, v235, v147, s[42:43]
	global_store_dwordx4 v[224:225], v[148:151], off
	global_store_dwordx4 v[250:251], v[232:235], off
	s_mov_b64 s[10:11], 0x18000
	v_lshl_add_u64 v[224:225], v[212:213], 0, s[10:11]
	s_mov_b64 s[10:11], 0x18000
	v_lshl_add_u64 v[250:251], v[252:253], 0, s[10:11]
	v_mov_b32_dpp v232, v156 row_ror:8 row_mask:0xf bank_mask:0xf
	v_mov_b32_dpp v233, v157 row_ror:8 row_mask:0xf bank_mask:0xf
	v_mov_b32_dpp v234, v158 row_ror:8 row_mask:0xf bank_mask:0xf
	v_mov_b32_dpp v235, v159 row_ror:8 row_mask:0xf bank_mask:0xf
	v_cndmask_b32_e64 v156, v152, v232, s[42:43]
	v_cndmask_b32_e64 v157, v153, v233, s[42:43]
	v_cndmask_b32_e64 v158, v154, v234, s[42:43]
	v_cndmask_b32_e64 v159, v155, v235, s[42:43]
	v_cndmask_b32_e64 v232, v232, v152, s[42:43]
	v_cndmask_b32_e64 v233, v233, v153, s[42:43]
	v_cndmask_b32_e64 v234, v234, v154, s[42:43]
	v_cndmask_b32_e64 v235, v235, v155, s[42:43]
	global_store_dwordx4 v[224:225], v[156:159], off
	global_store_dwordx4 v[250:251], v[232:235], off
	s_nop 1
	s_waitcnt vmcnt(15)
	v_lshlrev_b32_e32 v216, 16, v124
	v_and_b32_e32 v217, 0xffff0000, v124
	v_lshlrev_b32_e32 v218, 16, v125
	v_and_b32_e32 v219, 0xffff0000, v125
	v_lshlrev_b32_e32 v220, 16, v126
	v_and_b32_e32 v221, 0xffff0000, v126
	v_lshlrev_b32_e32 v222, 16, v127
	v_and_b32_e32 v223, 0xffff0000, v127
	v_pk_mul_f32 v[60:61], v[60:61], v[216:217]
	v_pk_mul_f32 v[62:63], v[62:63], v[218:219]
	v_pk_mul_f32 v[56:57], v[56:57], v[220:221]
	v_pk_mul_f32 v[58:59], v[58:59], v[222:223]
	v_cvt_pk_bf16_f32 v124, v60, v61
	v_cvt_pk_bf16_f32 v125, v62, v63
	v_cvt_pk_bf16_f32 v126, v56, v57
	v_cvt_pk_bf16_f32 v127, v58, v59
	s_waitcnt vmcnt(14)
	v_lshlrev_b32_e32 v216, 16, v92
	v_and_b32_e32 v217, 0xffff0000, v92
	v_lshlrev_b32_e32 v218, 16, v93
	v_and_b32_e32 v219, 0xffff0000, v93
	v_lshlrev_b32_e32 v220, 16, v94
	v_and_b32_e32 v221, 0xffff0000, v94
	v_lshlrev_b32_e32 v222, 16, v95
	v_and_b32_e32 v223, 0xffff0000, v95
	v_pk_mul_f32 v[28:29], v[28:29], v[216:217]
	v_pk_mul_f32 v[30:31], v[30:31], v[218:219]
	v_pk_mul_f32 v[24:25], v[24:25], v[220:221]
	v_pk_mul_f32 v[26:27], v[26:27], v[222:223]
	v_cvt_pk_bf16_f32 v92, v28, v29
	v_cvt_pk_bf16_f32 v93, v30, v31
	v_cvt_pk_bf16_f32 v94, v24, v25
	v_cvt_pk_bf16_f32 v95, v26, v27
	s_waitcnt vmcnt(13)
	v_lshlrev_b32_e32 v216, 16, v116
	v_and_b32_e32 v217, 0xffff0000, v116
	v_lshlrev_b32_e32 v218, 16, v117
	v_and_b32_e32 v219, 0xffff0000, v117
	v_lshlrev_b32_e32 v220, 16, v118
	v_and_b32_e32 v221, 0xffff0000, v118
	v_lshlrev_b32_e32 v222, 16, v119
	v_and_b32_e32 v223, 0xffff0000, v119
	v_pk_mul_f32 v[52:53], v[52:53], v[216:217]
	v_pk_mul_f32 v[54:55], v[54:55], v[218:219]
	v_pk_mul_f32 v[48:49], v[48:49], v[220:221]
	v_pk_mul_f32 v[50:51], v[50:51], v[222:223]
	v_cvt_pk_bf16_f32 v116, v52, v53
	v_cvt_pk_bf16_f32 v117, v54, v55
	v_cvt_pk_bf16_f32 v118, v48, v49
	v_cvt_pk_bf16_f32 v119, v50, v51
	s_waitcnt vmcnt(12)
; __device__ __forceinline__ u32x4 pack8(const f32x4& a, const f32x4& b) { u32x4 w; w.x = pk2(a[0], a[1]); w.y = pk2(a[2], a[3]); w.z = pk2(b[0], b[1]); w.w = pk2(b[2], b[3]); return w; }
; __device__ __forceinline__ void unpack8(const u32x4& w, f32x4& a, f32x4& b) { a[0] = bflo(w.x); a[1] = bfhi(w.x); a[2] = bflo(w.y); a[3] = bfhi(w.y); b[0] = bflo(w.z); b[1] = bfhi(w.z); b[2] = bflo(w.w); b[3] = bfhi(w.w); }
;     __device__ __forceinline__ void operator()(const f32x4 (&acc)[2][2][4][2], const Unit& u, int wr, int wc, int fr, int fq) const {
;     ...
;             bf16_t* const MRG = (bf16_t*)(ws + WS_SLAB + (size_t)(u.pm >> 4) * SLAB + SL_MRG); const int lrow0 = row0 & (SEQ - 1);
; #pragma unroll
;             for (int ai = 0; ai < 2; ++ai) {
;                 u32x4 gw[4][2], pw[4][2];
; #pragma unroll
;                 for (int m = 0; m < 4; ++m)
; #pragma unroll
;                     for (int bj = 0; bj < 2; ++bj) { gw[m][bj] = *(const u32x4*)(tmpb + ((ai * 4 + m) * 2 + bj) * 8192 + voff);
;                         if (br > 0) pw[m][bj] = *(const u32x4*)(MRG + (size_t)(lrow0 + ai * HALF + m * 16) * 1024 + col0 + 128 * bj); }
; #pragma unroll
;                 for (int m = 0; m < 4; ++m)
; #pragma unroll
;                     for (int bj = 0; bj < 2; ++bj) { f32x4 g0, g1; unpack8(gw[m][bj], g0, g1);
;                         f32x4 v0 = acc[ai][bj][m][0] * g0, v1 = acc[ai][bj][m][1] * g1;
;                         if (br > 0) { f32x4 p0, p1; unpack8(pw[m][bj], p0, p1); v0 += p0; v1 += p1; }
;                         *(u32x4*)(MRG + (size_t)(lrow0 + ai * HALF + m * 16) * 1024 + col0 + 128 * bj) = pack8(v0, v1); }
;                 asm volatile("" ::: "memory"); }
	v_lshlrev_b32_e32 v216, 16, v84
	v_and_b32_e32 v217, 0xffff0000, v84
	v_lshlrev_b32_e32 v218, 16, v85
	v_and_b32_e32 v219, 0xffff0000, v85
	v_lshlrev_b32_e32 v220, 16, v86
	v_and_b32_e32 v221, 0xffff0000, v86
	v_lshlrev_b32_e32 v222, 16, v87
	v_and_b32_e32 v223, 0xffff0000, v87
	v_pk_mul_f32 v[20:21], v[20:21], v[216:217]
	v_pk_mul_f32 v[22:23], v[22:23], v[218:219]
	v_pk_mul_f32 v[16:17], v[16:17], v[220:221]
	v_pk_mul_f32 v[18:19], v[18:19], v[222:223]
	v_cvt_pk_bf16_f32 v84, v20, v21
	v_cvt_pk_bf16_f32 v85, v22, v23
	v_cvt_pk_bf16_f32 v86, v16, v17
	v_cvt_pk_bf16_f32 v87, v18, v19
	s_mov_b64 s[10:11], 0x40000
	v_lshl_add_u64 v[224:225], v[212:213], 0, s[10:11]
	s_mov_b64 s[10:11], 0x40000
	v_lshl_add_u64 v[250:251], v[252:253], 0, s[10:11]
	v_mov_b32_dpp v232, v92 row_ror:8 row_mask:0xf bank_mask:0xf
	v_mov_b32_dpp v233, v93 row_ror:8 row_mask:0xf bank_mask:0xf
	v_mov_b32_dpp v234, v94 row_ror:8 row_mask:0xf bank_mask:0xf
	v_mov_b32_dpp v235, v95 row_ror:8 row_mask:0xf bank_mask:0xf
	v_cndmask_b32_e64 v92, v124, v232, s[42:43]
	v_cndmask_b32_e64 v93, v125, v233, s[42:43]
	v_cndmask_b32_e64 v94, v126, v234, s[42:43]
	v_cndmask_b32_e64 v95, v127, v235, s[42:43]
	v_cndmask_b32_e64 v232, v232, v124, s[42:43]
	v_cndmask_b32_e64 v233, v233, v125, s[42:43]
	v_cndmask_b32_e64 v234, v234, v126, s[42:43]
	v_cndmask_b32_e64 v235, v235, v127, s[42:43]
	global_store_dwordx4 v[224:225], v[92:95], off
	global_store_dwordx4 v[250:251], v[232:235], off
	s_mov_b64 s[10:11], 0x48000
	v_lshl_add_u64 v[224:225], v[212:213], 0, s[10:11]
	s_mov_b64 s[10:11], 0x48000
	v_lshl_add_u64 v[250:251], v[252:253], 0, s[10:11]
	v_mov_b32_dpp v232, v84 row_ror:8 row_mask:0xf bank_mask:0xf
	v_mov_b32_dpp v233, v85 row_ror:8 row_mask:0xf bank_mask:0xf
	v_mov_b32_dpp v234, v86 row_ror:8 row_mask:0xf bank_mask:0xf
	v_mov_b32_dpp v235, v87 row_ror:8 row_mask:0xf bank_mask:0xf
	v_cndmask_b32_e64 v84, v116, v232, s[42:43]
	v_cndmask_b32_e64 v85, v117, v233, s[42:43]
	v_cndmask_b32_e64 v86, v118, v234, s[42:43]
	v_cndmask_b32_e64 v87, v119, v235, s[42:43]
	v_cndmask_b32_e64 v232, v232, v116, s[42:43]
	v_cndmask_b32_e64 v233, v233, v117, s[42:43]
	v_cndmask_b32_e64 v234, v234, v118, s[42:43]
	v_cndmask_b32_e64 v235, v235, v119, s[42:43]
	global_store_dwordx4 v[224:225], v[84:87], off
	global_store_dwordx4 v[250:251], v[232:235], off
	s_nop 1
	s_waitcnt vmcnt(11)
	v_lshlrev_b32_e32 v216, 16, v108
	v_and_b32_e32 v217, 0xffff0000, v108
	v_lshlrev_b32_e32 v218, 16, v109
	v_and_b32_e32 v219, 0xffff0000, v109
	v_lshlrev_b32_e32 v220, 16, v110
	v_and_b32_e32 v221, 0xffff0000, v110
	v_lshlrev_b32_e32 v222, 16, v111
	v_and_b32_e32 v223, 0xffff0000, v111
	v_pk_mul_f32 v[44:45], v[44:45], v[216:217]
	v_pk_mul_f32 v[46:47], v[46:47], v[218:219]
	v_pk_mul_f32 v[40:41], v[40:41], v[220:221]
	v_pk_mul_f32 v[42:43], v[42:43], v[222:223]
	v_cvt_pk_bf16_f32 v108, v44, v45
	v_cvt_pk_bf16_f32 v109, v46, v47
	v_cvt_pk_bf16_f32 v110, v40, v41
	v_cvt_pk_bf16_f32 v111, v42, v43
	s_waitcnt vmcnt(10)
	v_lshlrev_b32_e32 v216, 16, v76
	v_and_b32_e32 v217, 0xffff0000, v76
	v_lshlrev_b32_e32 v218, 16, v77
	v_and_b32_e32 v219, 0xffff0000, v77
	v_lshlrev_b32_e32 v220, 16, v78
	v_and_b32_e32 v221, 0xffff0000, v78
	v_lshlrev_b32_e32 v222, 16, v79
	v_and_b32_e32 v223, 0xffff0000, v79
	v_pk_mul_f32 v[12:13], v[12:13], v[216:217]
	v_pk_mul_f32 v[14:15], v[14:15], v[218:219]
	v_pk_mul_f32 v[8:9], v[8:9], v[220:221]
	v_pk_mul_f32 v[10:11], v[10:11], v[222:223]
	v_cvt_pk_bf16_f32 v76, v12, v13
	v_cvt_pk_bf16_f32 v77, v14, v15
	v_cvt_pk_bf16_f32 v78, v8, v9
	v_cvt_pk_bf16_f32 v79, v10, v11
	s_waitcnt vmcnt(9)
	v_lshlrev_b32_e32 v216, 16, v100
	v_and_b32_e32 v217, 0xffff0000, v100
	v_lshlrev_b32_e32 v218, 16, v101
	v_and_b32_e32 v219, 0xffff0000, v101
	v_lshlrev_b32_e32 v220, 16, v102
	v_and_b32_e32 v221, 0xffff0000, v102
	v_lshlrev_b32_e32 v222, 16, v103
	v_and_b32_e32 v223, 0xffff0000, v103
	v_pk_mul_f32 v[36:37], v[36:37], v[216:217]
	v_pk_mul_f32 v[38:39], v[38:39], v[218:219]
	v_pk_mul_f32 v[32:33], v[32:33], v[220:221]
	v_pk_mul_f32 v[34:35], v[34:35], v[222:223]
	v_cvt_pk_bf16_f32 v100, v36, v37
	v_cvt_pk_bf16_f32 v101, v38, v39
	v_cvt_pk_bf16_f32 v102, v32, v33
	v_cvt_pk_bf16_f32 v103, v34, v35
	s_waitcnt vmcnt(8)
	v_lshlrev_b32_e32 v216, 16, v68
	v_and_b32_e32 v217, 0xffff0000, v68
	v_lshlrev_b32_e32 v218, 16, v69
	v_and_b32_e32 v219, 0xffff0000, v69
	v_lshlrev_b32_e32 v220, 16, v70
	v_and_b32_e32 v221, 0xffff0000, v70
	v_lshlrev_b32_e32 v222, 16, v71
	v_and_b32_e32 v223, 0xffff0000, v71
	v_pk_mul_f32 v[4:5], v[4:5], v[216:217]
	v_pk_mul_f32 v[6:7], v[6:7], v[218:219]
	v_pk_mul_f32 v[0:1], v[0:1], v[220:221]
	v_pk_mul_f32 v[2:3], v[2:3], v[222:223]
	v_cvt_pk_bf16_f32 v68, v4, v5
	v_cvt_pk_bf16_f32 v69, v6, v7
	v_cvt_pk_bf16_f32 v70, v0, v1
	v_cvt_pk_bf16_f32 v71, v2, v3
	s_mov_b64 s[10:11], 0x50000
	v_lshl_add_u64 v[224:225], v[212:213], 0, s[10:11]
	s_mov_b64 s[10:11], 0x50000
	v_lshl_add_u64 v[250:251], v[252:253], 0, s[10:11]
	v_mov_b32_dpp v232, v76 row_ror:8 row_mask:0xf bank_mask:0xf
	v_mov_b32_dpp v233, v77 row_ror:8 row_mask:0xf bank_mask:0xf
	v_mov_b32_dpp v234, v78 row_ror:8 row_mask:0xf bank_mask:0xf
	v_mov_b32_dpp v235, v79 row_ror:8 row_mask:0xf bank_mask:0xf
	v_cndmask_b32_e64 v76, v108, v232, s[42:43]
	v_cndmask_b32_e64 v77, v109, v233, s[42:43]
	v_cndmask_b32_e64 v78, v110, v234, s[42:43]
	v_cndmask_b32_e64 v79, v111, v235, s[42:43]
	v_cndmask_b32_e64 v232, v232, v108, s[42:43]
	v_cndmask_b32_e64 v233, v233, v109, s[42:43]
	v_cndmask_b32_e64 v234, v234, v110, s[42:43]
	v_cndmask_b32_e64 v235, v235, v111, s[42:43]
	global_store_dwordx4 v[224:225], v[76:79], off
	global_store_dwordx4 v[250:251], v[232:235], off
	s_mov_b64 s[10:11], 0x58000
	v_lshl_add_u64 v[224:225], v[212:213], 0, s[10:11]
	s_mov_b64 s[10:11], 0x58000
	v_lshl_add_u64 v[250:251], v[252:253], 0, s[10:11]
	v_mov_b32_dpp v232, v68 row_ror:8 row_mask:0xf bank_mask:0xf
	v_mov_b32_dpp v233, v69 row_ror:8 row_mask:0xf bank_mask:0xf
	v_mov_b32_dpp v234, v70 row_ror:8 row_mask:0xf bank_mask:0xf
	v_mov_b32_dpp v235, v71 row_ror:8 row_mask:0xf bank_mask:0xf
	v_cndmask_b32_e64 v68, v100, v232, s[42:43]
	v_cndmask_b32_e64 v69, v101, v233, s[42:43]
	v_cndmask_b32_e64 v70, v102, v234, s[42:43]
	v_cndmask_b32_e64 v71, v103, v235, s[42:43]
	v_cndmask_b32_e64 v232, v232, v100, s[42:43]
	v_cndmask_b32_e64 v233, v233, v101, s[42:43]
	v_cndmask_b32_e64 v234, v234, v102, s[42:43]
	v_cndmask_b32_e64 v235, v235, v103, s[42:43]
	global_store_dwordx4 v[224:225], v[68:71], off
	global_store_dwordx4 v[250:251], v[232:235], off
	s_nop 1
	s_branch .Le2_done
